# version 96 plus the same tail-prefetch skip in the gate|up and in-proj loops (last K-iteration of a workgroup's last unit)
# speedup vs baseline: 1.0147x; 1.0050x over previous
; #define PG8_STAGE(bufoff, gbase, voff) do { _Pragma("unroll") for (int _i = 0; _i < 2; ++_i) \
;         __builtin_amdgcn_global_load_lds((const unsigned*)((const char*)(gbase) + (voff)[_i]), (PG8_LAS unsigned*)(lds + (bufoff) + ldsw + _i * 8192), 16, 0, 0); } while (0)
; #define PG8_LDA(dst, b, h) do { _Pragma("unroll") for (int m = 0; m < 4; ++m) _Pragma("unroll") for (int k = 0; k < 2; ++k) dst[m][k] = *(const PG8_LAS bf16x8*)(lds + PG8_SA(b, h) + aoff + m * 2048 + k * 1024); } while (0)
; #define PG8_LDB(dst, b, h) do { _Pragma("unroll") for (int n = 0; n < 2; ++n) _Pragma("unroll") for (int k = 0; k < 2; ++k) dst[n][k] = *(const PG8_LAS bf16x8*)(lds + PG8_SB(b, h) + boff + n * 2048 + k * 1024); } while (0)
; #define PG8_MMA(ai, bj, At, Bt) do { __builtin_amdgcn_s_setprio(1); _Pragma("unroll") for (int m = 0; m < 4; ++m) _Pragma("unroll") for (int n = 0; n < 2; ++n) _Pragma("unroll") for (int k = 0; k < 2; ++k) \
;         acc[ai][bj][m][n] = __builtin_amdgcn_mfma_f32_16x16x32_bf16(Bt[n][k], At[m][k], acc[ai][bj][m][n], 0, 0, 0); __builtin_amdgcn_s_setprio(0); } while (0)
; #define PG8_WAIT_V(n) asm volatile("s_waitcnt vmcnt(" #n ")" ::: "memory")
; #define PG8_WAIT_L(n) asm volatile("s_waitcnt lgkmcnt(" #n ")" ::: "memory")
; #define PG8_BAR __builtin_amdgcn_s_barrier()
; #define PG8_SCHED __builtin_amdgcn_sched_barrier(0)
; template <class Epi, class Sched, bool ALIGN_EPI = false, bool SP2 = false>
; __device__ __forceinline__ void gemm_phase(PG8_LAS unsigned char* lds, const Gemm g, const Sched& S, const Epi& E, const int tid_in) {
;     ...
;             const bool last = (t == nt - 2);
;             const char* a1 = cA + (size_t)(t + 1) * kstep;
;             const char* a2 = last ? nA : cA + (size_t)(t + 2) * kstep; const char* b2 = last ? nB : cB + (size_t)(t + 2) * kstep;
;             const char* a3 = a2 + kstep; const char* b3 = b2 + kstep;
;             if (last && has_next) S.a_ready(nxt);
;             if constexpr (SP2) {
;             PG8_LDB(B0, 0, 0); PG8_LDB(B1, 0, 1); PG8_SCHED; PG8_LDA(At, 0, 0); PG8_STAGE(PG8_SA(1, 1), a1 + hstep, voffA);
;             PG8_WAIT_V(8); PG8_WAIT_L(0); PG8_BAR; PG8_MMA(0, 0, At, B0); PG8_MMA(0, 1, At, B1); PG8_BAR; PG8_SCHED;
;             PG8_LDA(At, 0, 1); PG8_STAGE(PG8_SB(0, 0), b2, voffB); PG8_STAGE(PG8_SB(0, 1), b2 + hstep, voffB); PG8_STAGE(PG8_SA(0, 0), a2, voffA);
.LBB0_93:
	s_add_u32 s12, s42, 0xfffc0080
	s_addc_u32 s13, s43, -1
	s_add_i32 s46, 0, 0x10000
	s_cmp_eq_u32 s45, 12
	s_cselect_b32 s15, s11, s13
	s_cselect_b32 s14, s16, s12
	v_add_u32_e32 v148, s46, v150
	s_cselect_b32 s13, s17, s39
	s_cselect_b32 s12, s21, s25
	s_cselect_b64 vcc, exec, 0
	s_andn2_b64 vcc, vcc, s[36:37]
	s_add_i32 s48, 0, 0x14000
	ds_read_b128 v[144:147], v148
	ds_read_b128 v[154:157], v148 offset:1024
	ds_read_b128 v[158:161], v148 offset:2048
	ds_read_b128 v[162:165], v148 offset:3072
	v_add_u32_e32 v148, s48, v150
	ds_read_b128 v[166:169], v148
	ds_read_b128 v[170:173], v148 offset:1024
	ds_read_b128 v[174:177], v148 offset:2048
	ds_read_b128 v[178:181], v148 offset:3072
	v_lshl_add_u64 v[148:149], s[42:43], 0, v[140:141]
	s_add_i32 m0, s22, 0xc000
	ds_read_b128 v[182:185], v152
	ds_read_b128 v[186:189], v152 offset:1024
	ds_read_b128 v[190:193], v152 offset:2048
	ds_read_b128 v[198:201], v152 offset:3072
	ds_read_b128 v[202:205], v152 offset:4096
	ds_read_b128 v[206:209], v152 offset:5120
	ds_read_b128 v[210:213], v152 offset:6144
	ds_read_b128 v[214:217], v152 offset:7168
	global_load_lds_dwordx4 v[148:149], off
	v_lshl_add_u64 v[148:149], s[42:43], 0, v[142:143]
	s_add_i32 m0, s22, 0xe000
	s_nop 0
	global_load_lds_dwordx4 v[148:149], off
	s_nop 0
	s_waitcnt vmcnt(8)
	s_waitcnt lgkmcnt(0)
	s_barrier
	v_mfma_f32_16x16x32_bf16 v[130:133], v[144:147], v[182:185], v[130:133]
	v_mfma_f32_16x16x32_bf16 v[130:133], v[154:157], v[186:189], v[130:133]
	v_mfma_f32_16x16x32_bf16 v[114:117], v[144:147], v[190:193], v[114:117]
	v_mfma_f32_16x16x32_bf16 v[114:117], v[154:157], v[198:201], v[114:117]
	v_mfma_f32_16x16x32_bf16 v[98:101], v[144:147], v[202:205], v[98:101]
	v_mfma_f32_16x16x32_bf16 v[98:101], v[154:157], v[206:209], v[98:101]
	v_mfma_f32_16x16x32_bf16 v[82:85], v[144:147], v[210:213], v[82:85]
	v_mfma_f32_16x16x32_bf16 v[82:85], v[154:157], v[214:217], v[82:85]
	v_mfma_f32_16x16x32_bf16 v[126:129], v[158:161], v[182:185], v[126:129]
	v_mfma_f32_16x16x32_bf16 v[126:129], v[162:165], v[186:189], v[126:129]
	v_mfma_f32_16x16x32_bf16 v[110:113], v[158:161], v[190:193], v[110:113]
	v_mfma_f32_16x16x32_bf16 v[110:113], v[162:165], v[198:201], v[110:113]
	v_mfma_f32_16x16x32_bf16 v[94:97], v[158:161], v[202:205], v[94:97]
	v_mfma_f32_16x16x32_bf16 v[94:97], v[162:165], v[206:209], v[94:97]
	v_mfma_f32_16x16x32_bf16 v[78:81], v[158:161], v[210:213], v[78:81]
	v_mfma_f32_16x16x32_bf16 v[78:81], v[162:165], v[214:217], v[78:81]
	v_mfma_f32_16x16x32_bf16 v[122:125], v[166:169], v[182:185], v[122:125]
	v_mfma_f32_16x16x32_bf16 v[122:125], v[170:173], v[186:189], v[122:125]
	v_mfma_f32_16x16x32_bf16 v[106:109], v[166:169], v[190:193], v[106:109]
	v_mfma_f32_16x16x32_bf16 v[106:109], v[170:173], v[198:201], v[106:109]
	v_mfma_f32_16x16x32_bf16 v[90:93], v[166:169], v[202:205], v[90:93]
	v_mfma_f32_16x16x32_bf16 v[90:93], v[170:173], v[206:209], v[90:93]
	v_mfma_f32_16x16x32_bf16 v[74:77], v[166:169], v[210:213], v[74:77]
	v_mfma_f32_16x16x32_bf16 v[74:77], v[170:173], v[214:217], v[74:77]
	v_mfma_f32_16x16x32_bf16 v[118:121], v[174:177], v[182:185], v[118:121]
	v_mfma_f32_16x16x32_bf16 v[118:121], v[178:181], v[186:189], v[118:121]
	v_mfma_f32_16x16x32_bf16 v[102:105], v[174:177], v[190:193], v[102:105]
	v_mfma_f32_16x16x32_bf16 v[102:105], v[178:181], v[198:201], v[102:105]
	v_mfma_f32_16x16x32_bf16 v[86:89], v[174:177], v[202:205], v[86:89]
	v_mfma_f32_16x16x32_bf16 v[86:89], v[178:181], v[206:209], v[86:89]
	v_mfma_f32_16x16x32_bf16 v[70:73], v[174:177], v[210:213], v[70:73]
	v_mfma_f32_16x16x32_bf16 v[70:73], v[178:181], v[214:217], v[70:73]
	s_barrier
	s_add_i32 s46, s46, s19
	v_lshl_add_u64 v[148:149], s[12:13], 0, v[134:135]
	s_mov_b32 m0, s46
	ds_read_b128 v[182:185], v152 offset:16384
	ds_read_b128 v[186:189], v152 offset:17408
	ds_read_b128 v[190:193], v152 offset:18432
	ds_read_b128 v[198:201], v152 offset:19456
	ds_read_b128 v[202:205], v152 offset:20480
	ds_read_b128 v[206:209], v152 offset:21504
	ds_read_b128 v[210:213], v152 offset:22528
	ds_read_b128 v[214:217], v152 offset:23552
	s_cbranch_vccnz .Ltsin_skip_1
	global_load_lds_dwordx4 v[148:149], off
	s_add_i32 m0, s46, 0x2000
	s_add_u32 s46, s12, 0x40000
	v_lshl_add_u64 v[218:219], s[12:13], 0, v[138:139]
	s_addc_u32 s47, s13, 0
	s_add_i32 s48, s48, s19
	global_load_lds_dwordx4 v[218:219], off
	v_lshl_add_u64 v[220:221], s[46:47], 0, v[134:135]
	s_mov_b32 m0, s48
	v_lshl_add_u64 v[222:223], s[14:15], 0, v[136:137]
	global_load_lds_dwordx4 v[220:221], off
	v_lshl_add_u64 v[220:221], s[46:47], 0, v[138:139]
	s_add_i32 m0, s48, 0x2000
	s_nop 0
	global_load_lds_dwordx4 v[220:221], off
	v_lshl_add_u64 v[220:221], s[14:15], 0, v[2:3]
	s_mov_b32 m0, s22
	s_nop 0
	global_load_lds_dwordx4 v[220:221], off
	s_mov_b32 m0, s23
	s_nop 0
	global_load_lds_dwordx4 v[222:223], off
	s_nop 0
	s_waitcnt vmcnt(8)
	s_branch .Ltsin_join_1

; #define PG8_STAGE(bufoff, gbase, voff) do { _Pragma("unroll") for (int _i = 0; _i < 2; ++_i) \
;         __builtin_amdgcn_global_load_lds((const unsigned*)((const char*)(gbase) + (voff)[_i]), (PG8_LAS unsigned*)(lds + (bufoff) + ldsw + _i * 8192), 16, 0, 0); } while (0)
; #define PG8_LDA(dst, b, h) do { _Pragma("unroll") for (int m = 0; m < 4; ++m) _Pragma("unroll") for (int k = 0; k < 2; ++k) dst[m][k] = *(const PG8_LAS bf16x8*)(lds + PG8_SA(b, h) + aoff + m * 2048 + k * 1024); } while (0)
; #define PG8_LDB(dst, b, h) do { _Pragma("unroll") for (int n = 0; n < 2; ++n) _Pragma("unroll") for (int k = 0; k < 2; ++k) dst[n][k] = *(const PG8_LAS bf16x8*)(lds + PG8_SB(b, h) + boff + n * 2048 + k * 1024); } while (0)
; #define PG8_MMA(ai, bj, At, Bt) do { __builtin_amdgcn_s_setprio(1); _Pragma("unroll") for (int m = 0; m < 4; ++m) _Pragma("unroll") for (int n = 0; n < 2; ++n) _Pragma("unroll") for (int k = 0; k < 2; ++k) \
;         acc[ai][bj][m][n] = __builtin_amdgcn_mfma_f32_16x16x32_bf16(Bt[n][k], At[m][k], acc[ai][bj][m][n], 0, 0, 0); __builtin_amdgcn_s_setprio(0); } while (0)
; #define PG8_WAIT_V(n) asm volatile("s_waitcnt vmcnt(" #n ")" ::: "memory")
; #define PG8_WAIT_L(n) asm volatile("s_waitcnt lgkmcnt(" #n ")" ::: "memory")
; #define PG8_BAR __builtin_amdgcn_s_barrier()
; #define PG8_SCHED __builtin_amdgcn_sched_barrier(0)
; template <class Epi, class Sched, bool ALIGN_EPI = false, bool SP2 = false>
; __device__ __forceinline__ void gemm_phase(PG8_LAS unsigned char* lds, const Gemm g, const Sched& S, const Epi& E, const int tid_in) {
;     ...
;             PG8_LDA(At, 0, 1); PG8_STAGE(PG8_SB(0, 0), b2, voffB); PG8_STAGE(PG8_SB(0, 1), b2 + hstep, voffB); PG8_STAGE(PG8_SA(0, 0), a2, voffA);
;             PG8_WAIT_V(8); PG8_WAIT_L(0); PG8_BAR; PG8_MMA(1, 0, At, B0); PG8_MMA(1, 1, At, B1); PG8_BAR; PG8_SCHED;
;             PG8_LDB(B0, 1, 0); PG8_LDB(B1, 1, 1); PG8_SCHED; PG8_LDA(At, 1, 0); PG8_STAGE(PG8_SA(0, 1), a2 + hstep, voffA);
;             PG8_WAIT_V(8); PG8_WAIT_L(0); PG8_BAR; PG8_MMA(0, 0, At, B0); PG8_MMA(0, 1, At, B1); PG8_BAR; PG8_SCHED;
.Ltsin_join_1:
	s_waitcnt lgkmcnt(0)
	s_barrier
	v_mfma_f32_16x16x32_bf16 v[66:69], v[144:147], v[182:185], v[66:69]
	v_mfma_f32_16x16x32_bf16 v[66:69], v[154:157], v[186:189], v[66:69]
	v_mfma_f32_16x16x32_bf16 v[50:53], v[144:147], v[190:193], v[50:53]
	v_mfma_f32_16x16x32_bf16 v[50:53], v[154:157], v[198:201], v[50:53]
	v_mfma_f32_16x16x32_bf16 v[34:37], v[144:147], v[202:205], v[34:37]
	v_mfma_f32_16x16x32_bf16 v[34:37], v[154:157], v[206:209], v[34:37]
	v_mfma_f32_16x16x32_bf16 v[18:21], v[144:147], v[210:213], v[18:21]
	v_mfma_f32_16x16x32_bf16 v[18:21], v[154:157], v[214:217], v[18:21]
	v_mfma_f32_16x16x32_bf16 v[62:65], v[158:161], v[182:185], v[62:65]
	v_mfma_f32_16x16x32_bf16 v[62:65], v[162:165], v[186:189], v[62:65]
	v_mfma_f32_16x16x32_bf16 v[46:49], v[158:161], v[190:193], v[46:49]
	v_mfma_f32_16x16x32_bf16 v[46:49], v[162:165], v[198:201], v[46:49]
	v_mfma_f32_16x16x32_bf16 v[30:33], v[158:161], v[202:205], v[30:33]
	v_mfma_f32_16x16x32_bf16 v[30:33], v[162:165], v[206:209], v[30:33]
	v_mfma_f32_16x16x32_bf16 v[14:17], v[158:161], v[210:213], v[14:17]
	v_mfma_f32_16x16x32_bf16 v[14:17], v[162:165], v[214:217], v[14:17]
	v_mfma_f32_16x16x32_bf16 v[58:61], v[166:169], v[182:185], v[58:61]
	v_mfma_f32_16x16x32_bf16 v[58:61], v[170:173], v[186:189], v[58:61]
	v_mfma_f32_16x16x32_bf16 v[42:45], v[166:169], v[190:193], v[42:45]
	v_mfma_f32_16x16x32_bf16 v[42:45], v[170:173], v[198:201], v[42:45]
	v_mfma_f32_16x16x32_bf16 v[26:29], v[166:169], v[202:205], v[26:29]
	v_mfma_f32_16x16x32_bf16 v[26:29], v[170:173], v[206:209], v[26:29]
	v_mfma_f32_16x16x32_bf16 v[10:13], v[166:169], v[210:213], v[10:13]
	v_mfma_f32_16x16x32_bf16 v[10:13], v[170:173], v[214:217], v[10:13]
	v_mfma_f32_16x16x32_bf16 v[54:57], v[174:177], v[182:185], v[54:57]
	v_mfma_f32_16x16x32_bf16 v[54:57], v[178:181], v[186:189], v[54:57]
	v_mfma_f32_16x16x32_bf16 v[38:41], v[174:177], v[190:193], v[38:41]
	v_mfma_f32_16x16x32_bf16 v[38:41], v[178:181], v[198:201], v[38:41]
	v_mfma_f32_16x16x32_bf16 v[22:25], v[174:177], v[202:205], v[22:25]
	v_mfma_f32_16x16x32_bf16 v[22:25], v[178:181], v[206:209], v[22:25]
	v_mfma_f32_16x16x32_bf16 v[6:9], v[174:177], v[210:213], v[6:9]
	v_mfma_f32_16x16x32_bf16 v[6:9], v[178:181], v[214:217], v[6:9]
	s_barrier
	s_add_i32 s46, 0, 0x18000
	v_add_u32_e32 v153, s46, v150
	s_add_i32 s47, 0, 0x1c000
	ds_read_b128 v[144:147], v153
	ds_read_b128 v[154:157], v153 offset:1024
	ds_read_b128 v[158:161], v153 offset:2048
	ds_read_b128 v[162:165], v153 offset:3072
	v_add_u32_e32 v153, s47, v150
	ds_read_b128 v[166:169], v153
	ds_read_b128 v[170:173], v153 offset:1024
	ds_read_b128 v[174:177], v153 offset:2048
	ds_read_b128 v[178:181], v153 offset:3072
	s_add_u32 s14, s14, 0x40000
	s_addc_u32 s15, s15, 0
	s_mov_b32 m0, s26
	v_lshl_add_u64 v[224:225], s[14:15], 0, v[2:3]
	ds_read_b128 v[182:185], v152 offset:32768
	ds_read_b128 v[186:189], v152 offset:33792
	ds_read_b128 v[190:193], v152 offset:34816
	ds_read_b128 v[198:201], v152 offset:35840
	ds_read_b128 v[202:205], v152 offset:36864
	ds_read_b128 v[206:209], v152 offset:37888
	ds_read_b128 v[210:213], v152 offset:38912
	ds_read_b128 v[214:217], v152 offset:39936
	s_cbranch_vccnz .Ltsin_skip_2
	global_load_lds_dwordx4 v[224:225], off
	v_lshl_add_u64 v[224:225], s[14:15], 0, v[136:137]
	s_mov_b32 m0, s27
	s_nop 0
	global_load_lds_dwordx4 v[224:225], off
	s_nop 0
	s_waitcnt vmcnt(8)
	s_branch .Ltsin_join_2

; #define PG8_STAGE(bufoff, gbase, voff) do { _Pragma("unroll") for (int _i = 0; _i < 2; ++_i) \
;         __builtin_amdgcn_global_load_lds((const unsigned*)((const char*)(gbase) + (voff)[_i]), (PG8_LAS unsigned*)(lds + (bufoff) + ldsw + _i * 8192), 16, 0, 0); } while (0)
; #define PG8_LDA(dst, b, h) do { _Pragma("unroll") for (int m = 0; m < 4; ++m) _Pragma("unroll") for (int k = 0; k < 2; ++k) dst[m][k] = *(const PG8_LAS bf16x8*)(lds + PG8_SA(b, h) + aoff + m * 2048 + k * 1024); } while (0)
; #define PG8_MMA(ai, bj, At, Bt) do { __builtin_amdgcn_s_setprio(1); _Pragma("unroll") for (int m = 0; m < 4; ++m) _Pragma("unroll") for (int n = 0; n < 2; ++n) _Pragma("unroll") for (int k = 0; k < 2; ++k) \
;         acc[ai][bj][m][n] = __builtin_amdgcn_mfma_f32_16x16x32_bf16(Bt[n][k], At[m][k], acc[ai][bj][m][n], 0, 0, 0); __builtin_amdgcn_s_setprio(0); } while (0)
; #define PG8_WAIT_V(n) asm volatile("s_waitcnt vmcnt(" #n ")" ::: "memory")
; #define PG8_WAIT_L(n) asm volatile("s_waitcnt lgkmcnt(" #n ")" ::: "memory")
; #define PG8_BAR __builtin_amdgcn_s_barrier()
; #define PG8_SCHED __builtin_amdgcn_sched_barrier(0)
; template <class Epi, class Sched, bool ALIGN_EPI = false, bool SP2 = false>
; __device__ __forceinline__ void gemm_phase(PG8_LAS unsigned char* lds, const Gemm g, const Sched& S, const Epi& E, const int tid_in) {
;     ...
;             PG8_WAIT_V(8); PG8_WAIT_L(0); PG8_BAR; PG8_MMA(0, 0, At, B0); PG8_MMA(0, 1, At, B1); PG8_BAR; PG8_SCHED;
;             PG8_LDA(At, 1, 1); PG8_STAGE(PG8_SB(1, 0), b3, voffB); PG8_STAGE(PG8_SB(1, 1), b3 + hstep, voffB); PG8_STAGE(PG8_SA(1, 0), a3, voffA);
;             PG8_WAIT_V(8); PG8_WAIT_L(0); PG8_BAR; PG8_MMA(1, 0, At, B0); PG8_MMA(1, 1, At, B1); PG8_BAR; PG8_SCHED;
.Ltsin_join_2:
	s_waitcnt lgkmcnt(0)
	s_barrier
	v_mfma_f32_16x16x32_bf16 v[130:133], v[144:147], v[182:185], v[130:133]
	v_mfma_f32_16x16x32_bf16 v[130:133], v[154:157], v[186:189], v[130:133]
	v_mfma_f32_16x16x32_bf16 v[114:117], v[144:147], v[190:193], v[114:117]
	v_mfma_f32_16x16x32_bf16 v[114:117], v[154:157], v[198:201], v[114:117]
	v_mfma_f32_16x16x32_bf16 v[98:101], v[144:147], v[202:205], v[98:101]
	v_mfma_f32_16x16x32_bf16 v[98:101], v[154:157], v[206:209], v[98:101]
	v_mfma_f32_16x16x32_bf16 v[82:85], v[144:147], v[210:213], v[82:85]
	v_mfma_f32_16x16x32_bf16 v[82:85], v[154:157], v[214:217], v[82:85]
	v_mfma_f32_16x16x32_bf16 v[126:129], v[158:161], v[182:185], v[126:129]
	v_mfma_f32_16x16x32_bf16 v[126:129], v[162:165], v[186:189], v[126:129]
	v_mfma_f32_16x16x32_bf16 v[110:113], v[158:161], v[190:193], v[110:113]
	v_mfma_f32_16x16x32_bf16 v[110:113], v[162:165], v[198:201], v[110:113]
	v_mfma_f32_16x16x32_bf16 v[94:97], v[158:161], v[202:205], v[94:97]
	v_mfma_f32_16x16x32_bf16 v[94:97], v[162:165], v[206:209], v[94:97]
	v_mfma_f32_16x16x32_bf16 v[78:81], v[158:161], v[210:213], v[78:81]
	v_mfma_f32_16x16x32_bf16 v[78:81], v[162:165], v[214:217], v[78:81]
	v_mfma_f32_16x16x32_bf16 v[122:125], v[166:169], v[182:185], v[122:125]
	v_mfma_f32_16x16x32_bf16 v[122:125], v[170:173], v[186:189], v[122:125]
	v_mfma_f32_16x16x32_bf16 v[106:109], v[166:169], v[190:193], v[106:109]
	v_mfma_f32_16x16x32_bf16 v[106:109], v[170:173], v[198:201], v[106:109]
	v_mfma_f32_16x16x32_bf16 v[90:93], v[166:169], v[202:205], v[90:93]
	v_mfma_f32_16x16x32_bf16 v[90:93], v[170:173], v[206:209], v[90:93]
	v_mfma_f32_16x16x32_bf16 v[74:77], v[166:169], v[210:213], v[74:77]
	v_mfma_f32_16x16x32_bf16 v[74:77], v[170:173], v[214:217], v[74:77]
	v_mfma_f32_16x16x32_bf16 v[118:121], v[174:177], v[182:185], v[118:121]
	v_mfma_f32_16x16x32_bf16 v[118:121], v[178:181], v[186:189], v[118:121]
	v_mfma_f32_16x16x32_bf16 v[102:105], v[174:177], v[190:193], v[102:105]
	v_mfma_f32_16x16x32_bf16 v[102:105], v[178:181], v[198:201], v[102:105]
	v_mfma_f32_16x16x32_bf16 v[86:89], v[174:177], v[202:205], v[86:89]
	v_mfma_f32_16x16x32_bf16 v[86:89], v[178:181], v[206:209], v[86:89]
	v_mfma_f32_16x16x32_bf16 v[70:73], v[174:177], v[210:213], v[70:73]
	v_mfma_f32_16x16x32_bf16 v[70:73], v[178:181], v[214:217], v[70:73]
	s_barrier
	s_add_i32 s14, s46, s19
	v_lshl_add_u64 v[148:149], v[148:149], 0, s[28:29]
	s_mov_b32 m0, s14
	ds_read_b128 v[182:185], v152 offset:49152
	ds_read_b128 v[186:189], v152 offset:50176
	ds_read_b128 v[190:193], v152 offset:51200
	ds_read_b128 v[198:201], v152 offset:52224
	ds_read_b128 v[202:205], v152 offset:53248
	ds_read_b128 v[206:209], v152 offset:54272
	ds_read_b128 v[210:213], v152 offset:55296
	ds_read_b128 v[214:217], v152 offset:56320
	s_cbranch_vccnz .Ltsin_skip_3
	global_load_lds_dwordx4 v[148:149], off
	s_add_i32 m0, s14, 0x2000
	s_add_u32 s12, s12, 0x40080
	v_lshl_add_u64 v[148:149], v[218:219], 0, s[28:29]
	s_addc_u32 s13, s13, 0
	s_add_i32 s14, s47, s19
	global_load_lds_dwordx4 v[148:149], off
	v_lshl_add_u64 v[148:149], s[12:13], 0, v[134:135]
	s_mov_b32 m0, s14
	s_nop 0
	global_load_lds_dwordx4 v[148:149], off
	v_lshl_add_u64 v[148:149], s[12:13], 0, v[138:139]
	s_add_i32 m0, s14, 0x2000
	s_nop 0
	global_load_lds_dwordx4 v[148:149], off
	v_lshl_add_u64 v[148:149], v[220:221], 0, s[28:29]
	s_mov_b32 m0, s30
	s_nop 0
	global_load_lds_dwordx4 v[148:149], off
	v_lshl_add_u64 v[148:149], v[222:223], 0, s[28:29]
	s_mov_b32 m0, s31
	s_nop 0
	global_load_lds_dwordx4 v[148:149], off
	s_nop 0
	s_waitcnt vmcnt(8)
	s_branch .Ltsin_join_3

; #define PG8_STAGE(bufoff, gbase, voff) do { _Pragma("unroll") for (int _i = 0; _i < 2; ++_i) \
;         __builtin_amdgcn_global_load_lds((const unsigned*)((const char*)(gbase) + (voff)[_i]), (PG8_LAS unsigned*)(lds + (bufoff) + ldsw + _i * 8192), 16, 0, 0); } while (0)
; #define PG8_LDA(dst, b, h) do { _Pragma("unroll") for (int m = 0; m < 4; ++m) _Pragma("unroll") for (int k = 0; k < 2; ++k) dst[m][k] = *(const PG8_LAS bf16x8*)(lds + PG8_SA(b, h) + aoff + m * 2048 + k * 1024); } while (0)
; #define PG8_MMA(ai, bj, At, Bt) do { __builtin_amdgcn_s_setprio(1); _Pragma("unroll") for (int m = 0; m < 4; ++m) _Pragma("unroll") for (int n = 0; n < 2; ++n) _Pragma("unroll") for (int k = 0; k < 2; ++k) \
;         acc[ai][bj][m][n] = __builtin_amdgcn_mfma_f32_16x16x32_bf16(Bt[n][k], At[m][k], acc[ai][bj][m][n], 0, 0, 0); __builtin_amdgcn_s_setprio(0); } while (0)
; #define PG8_WAIT_V(n) asm volatile("s_waitcnt vmcnt(" #n ")" ::: "memory")
; #define PG8_WAIT_L(n) asm volatile("s_waitcnt lgkmcnt(" #n ")" ::: "memory")
; #define PG8_BAR __builtin_amdgcn_s_barrier()
; #define PG8_SCHED __builtin_amdgcn_sched_barrier(0)
; template <class Epi, class Sched, bool ALIGN_EPI = false, bool SP2 = false>
; __device__ __forceinline__ void gemm_phase(PG8_LAS unsigned char* lds, const Gemm g, const Sched& S, const Epi& E, const int tid_in) {
;     ...
;             PG8_LDA(At, 1, 1); PG8_STAGE(PG8_SB(1, 0), b3, voffB); PG8_STAGE(PG8_SB(1, 1), b3 + hstep, voffB); PG8_STAGE(PG8_SA(1, 0), a3, voffA);
;             PG8_WAIT_V(8); PG8_WAIT_L(0); PG8_BAR; PG8_MMA(1, 0, At, B0); PG8_MMA(1, 1, At, B1); PG8_BAR; PG8_SCHED;
;     __device__ __forceinline__ void operator()(const f32x4 (&acc)[2][2][4][2], const Unit& u, int wr, int wc, int fr, int fq) const {
;     ...
;         float rs[2][4];
; #pragma unroll
;         for (int ai = 0; ai < 2; ++ai)
; #pragma unroll
;             for (int m = 0; m < 4; ++m) rs[ai][m] = rowss[row0 + ai * HALF + m * 16];
.Ltsin_join_3:
	s_waitcnt lgkmcnt(0)
	s_cmp_lg_u32 s45, 12
	s_cbranch_scc1 .Lrs_in_skip
	v_lshl_add_u32 v148, s38, 8, v5
	v_ashrrev_i32_e32 v149, 31, v148
	v_lshl_add_u64 v[148:149], v[148:149], 2, s[6:7]
	global_load_dword v226, v[148:149], off
	global_load_dword v227, v[148:149], off offset:64
	global_load_dword v228, v[148:149], off offset:128
	global_load_dword v229, v[148:149], off offset:192
	global_load_dword v238, v[148:149], off offset:512
	global_load_dword v239, v[148:149], off offset:576
	global_load_dword v240, v[148:149], off offset:640
	global_load_dword v241, v[148:149], off offset:704

; #define PG8_STAGE(bufoff, gbase, voff) do { _Pragma("unroll") for (int _i = 0; _i < 2; ++_i) \
;         __builtin_amdgcn_global_load_lds((const unsigned*)((const char*)(gbase) + (voff)[_i]), (PG8_LAS unsigned*)(lds + (bufoff) + ldsw + _i * 8192), 16, 0, 0); } while (0)
; #define PG8_LDA(dst, b, h) do { _Pragma("unroll") for (int m = 0; m < 4; ++m) _Pragma("unroll") for (int k = 0; k < 2; ++k) dst[m][k] = *(const PG8_LAS bf16x8*)(lds + PG8_SA(b, h) + aoff + m * 2048 + k * 1024); } while (0)
; #define PG8_LDB(dst, b, h) do { _Pragma("unroll") for (int n = 0; n < 2; ++n) _Pragma("unroll") for (int k = 0; k < 2; ++k) dst[n][k] = *(const PG8_LAS bf16x8*)(lds + PG8_SB(b, h) + boff + n * 2048 + k * 1024); } while (0)
; #define PG8_MMA(ai, bj, At, Bt) do { __builtin_amdgcn_s_setprio(1); _Pragma("unroll") for (int m = 0; m < 4; ++m) _Pragma("unroll") for (int n = 0; n < 2; ++n) _Pragma("unroll") for (int k = 0; k < 2; ++k) \
;         acc[ai][bj][m][n] = __builtin_amdgcn_mfma_f32_16x16x32_bf16(Bt[n][k], At[m][k], acc[ai][bj][m][n], 0, 0, 0); __builtin_amdgcn_s_setprio(0); } while (0)
; #define PG8_WAIT_V(n) asm volatile("s_waitcnt vmcnt(" #n ")" ::: "memory")
; #define PG8_WAIT_L(n) asm volatile("s_waitcnt lgkmcnt(" #n ")" ::: "memory")
; #define PG8_BAR __builtin_amdgcn_s_barrier()
; #define PG8_SCHED __builtin_amdgcn_sched_barrier(0)
; template <class Epi, class Sched, bool ALIGN_EPI = false, bool SP2 = false>
; __device__ __forceinline__ void gemm_phase(PG8_LAS unsigned char* lds, const Gemm g, const Sched& S, const Epi& E, const int tid_in) {
;     ...
;             const bool last = (t == nt - 2);
;             const char* a1 = cA + (size_t)(t + 1) * kstep;
;             const char* a2 = last ? nA : cA + (size_t)(t + 2) * kstep; const char* b2 = last ? nB : cB + (size_t)(t + 2) * kstep;
;             const char* a3 = a2 + kstep; const char* b3 = b2 + kstep;
;             if (last && has_next) S.a_ready(nxt);
;             if constexpr (SP2) {
;             PG8_LDB(B0, 0, 0); PG8_LDB(B1, 0, 1); PG8_SCHED; PG8_LDA(At, 0, 0); PG8_STAGE(PG8_SA(1, 1), a1 + hstep, voffA);
;             PG8_WAIT_V(8); PG8_WAIT_L(0); PG8_BAR; PG8_MMA(0, 0, At, B0); PG8_MMA(0, 1, At, B1); PG8_BAR; PG8_SCHED;
;             PG8_LDA(At, 0, 1); PG8_STAGE(PG8_SB(0, 0), b2, voffB); PG8_STAGE(PG8_SB(0, 1), b2 + hstep, voffB); PG8_STAGE(PG8_SA(0, 0), a2, voffA);
.LBB0_154:
	s_add_u32 s12, s10, 0xfffc0080
	s_addc_u32 s13, s11, -1
	s_add_i32 s46, 0, 0x10000
	s_cmp_eq_u32 s45, 12
	s_cselect_b32 s15, s25, s13
	s_cselect_b32 s14, s41, s12
	v_add_u32_e32 v144, s46, v146
	s_cselect_b32 s13, s21, s44
	s_cselect_b32 s12, s42, s43
	s_cselect_b64 vcc, exec, 0
	s_andn2_b64 vcc, vcc, s[36:37]
	s_add_i32 s48, 0, 0x14000
	ds_read_b128 v[150:153], v144
	ds_read_b128 v[154:157], v144 offset:1024
	ds_read_b128 v[158:161], v144 offset:2048
	ds_read_b128 v[162:165], v144 offset:3072
	v_add_u32_e32 v144, s48, v146
	ds_read_b128 v[166:169], v144
	ds_read_b128 v[170:173], v144 offset:1024
	ds_read_b128 v[174:177], v144 offset:2048
	ds_read_b128 v[178:181], v144 offset:3072
	v_lshl_add_u64 v[144:145], s[10:11], 0, v[140:141]
	s_add_i32 m0, s18, 0xc000
	ds_read_b128 v[182:185], v148
	ds_read_b128 v[186:189], v148 offset:1024
	ds_read_b128 v[190:193], v148 offset:2048
	ds_read_b128 v[198:201], v148 offset:3072
	ds_read_b128 v[202:205], v148 offset:4096
	ds_read_b128 v[206:209], v148 offset:5120
	ds_read_b128 v[210:213], v148 offset:6144
	ds_read_b128 v[214:217], v148 offset:7168
	global_load_lds_dwordx4 v[144:145], off
	v_lshl_add_u64 v[144:145], s[10:11], 0, v[142:143]
	s_add_i32 m0, s18, 0xe000
	s_nop 0
	global_load_lds_dwordx4 v[144:145], off
	s_nop 0
	s_waitcnt vmcnt(8)
	s_waitcnt lgkmcnt(0)
	s_barrier
	v_mfma_f32_16x16x32_bf16 v[130:133], v[150:153], v[182:185], v[130:133]
	v_mfma_f32_16x16x32_bf16 v[130:133], v[154:157], v[186:189], v[130:133]
	v_mfma_f32_16x16x32_bf16 v[114:117], v[150:153], v[190:193], v[114:117]
	v_mfma_f32_16x16x32_bf16 v[114:117], v[154:157], v[198:201], v[114:117]
	v_mfma_f32_16x16x32_bf16 v[98:101], v[150:153], v[202:205], v[98:101]
	v_mfma_f32_16x16x32_bf16 v[98:101], v[154:157], v[206:209], v[98:101]
	v_mfma_f32_16x16x32_bf16 v[82:85], v[150:153], v[210:213], v[82:85]
	v_mfma_f32_16x16x32_bf16 v[82:85], v[154:157], v[214:217], v[82:85]
	v_mfma_f32_16x16x32_bf16 v[126:129], v[158:161], v[182:185], v[126:129]
	v_mfma_f32_16x16x32_bf16 v[126:129], v[162:165], v[186:189], v[126:129]
	v_mfma_f32_16x16x32_bf16 v[106:109], v[158:161], v[190:193], v[106:109]
	v_mfma_f32_16x16x32_bf16 v[106:109], v[162:165], v[198:201], v[106:109]
	v_mfma_f32_16x16x32_bf16 v[94:97], v[158:161], v[202:205], v[94:97]
	v_mfma_f32_16x16x32_bf16 v[94:97], v[162:165], v[206:209], v[94:97]
	v_mfma_f32_16x16x32_bf16 v[78:81], v[158:161], v[210:213], v[78:81]
	v_mfma_f32_16x16x32_bf16 v[78:81], v[162:165], v[214:217], v[78:81]
	v_mfma_f32_16x16x32_bf16 v[122:125], v[166:169], v[182:185], v[122:125]
	v_mfma_f32_16x16x32_bf16 v[122:125], v[170:173], v[186:189], v[122:125]
	v_mfma_f32_16x16x32_bf16 v[110:113], v[166:169], v[190:193], v[110:113]
	v_mfma_f32_16x16x32_bf16 v[110:113], v[170:173], v[198:201], v[110:113]
	v_mfma_f32_16x16x32_bf16 v[90:93], v[166:169], v[202:205], v[90:93]
	v_mfma_f32_16x16x32_bf16 v[90:93], v[170:173], v[206:209], v[90:93]
	v_mfma_f32_16x16x32_bf16 v[74:77], v[166:169], v[210:213], v[74:77]
	v_mfma_f32_16x16x32_bf16 v[74:77], v[170:173], v[214:217], v[74:77]
	v_mfma_f32_16x16x32_bf16 v[118:121], v[174:177], v[182:185], v[118:121]
	v_mfma_f32_16x16x32_bf16 v[118:121], v[178:181], v[186:189], v[118:121]
	v_mfma_f32_16x16x32_bf16 v[102:105], v[174:177], v[190:193], v[102:105]
	v_mfma_f32_16x16x32_bf16 v[102:105], v[178:181], v[198:201], v[102:105]
	v_mfma_f32_16x16x32_bf16 v[86:89], v[174:177], v[202:205], v[86:89]
	v_mfma_f32_16x16x32_bf16 v[86:89], v[178:181], v[206:209], v[86:89]
	v_mfma_f32_16x16x32_bf16 v[70:73], v[174:177], v[210:213], v[70:73]
	v_mfma_f32_16x16x32_bf16 v[70:73], v[178:181], v[214:217], v[70:73]
	s_barrier
	s_add_i32 s46, s46, s17
	v_lshl_add_u64 v[144:145], s[12:13], 0, v[136:137]
	s_mov_b32 m0, s46
	ds_read_b128 v[182:185], v148 offset:16384
	ds_read_b128 v[186:189], v148 offset:17408
	ds_read_b128 v[190:193], v148 offset:18432
	ds_read_b128 v[198:201], v148 offset:19456
	ds_read_b128 v[202:205], v148 offset:20480
	ds_read_b128 v[206:209], v148 offset:21504
	ds_read_b128 v[210:213], v148 offset:22528
	ds_read_b128 v[214:217], v148 offset:23552
	s_cbranch_vccnz .Ltsgu_skip_1
	global_load_lds_dwordx4 v[144:145], off
	s_add_i32 m0, s46, 0x2000
	s_add_u32 s46, s12, 0x40000
	v_lshl_add_u64 v[218:219], s[12:13], 0, v[2:3]
	s_addc_u32 s47, s13, 0
	s_add_i32 s48, s48, s17
	global_load_lds_dwordx4 v[218:219], off
	v_lshl_add_u64 v[220:221], s[46:47], 0, v[136:137]
	s_mov_b32 m0, s48
	v_lshl_add_u64 v[222:223], s[14:15], 0, v[134:135]
	global_load_lds_dwordx4 v[220:221], off
	v_lshl_add_u64 v[220:221], s[46:47], 0, v[2:3]
	s_add_i32 m0, s48, 0x2000
	s_nop 0
	global_load_lds_dwordx4 v[220:221], off
	v_lshl_add_u64 v[220:221], s[14:15], 0, v[138:139]
	s_mov_b32 m0, s18
	s_nop 0
	global_load_lds_dwordx4 v[220:221], off
	s_mov_b32 m0, s19
	s_nop 0
	global_load_lds_dwordx4 v[222:223], off
	s_nop 0
	s_waitcnt vmcnt(8)
	s_branch .Ltsgu_join_1

; #define PG8_STAGE(bufoff, gbase, voff) do { _Pragma("unroll") for (int _i = 0; _i < 2; ++_i) \
;         __builtin_amdgcn_global_load_lds((const unsigned*)((const char*)(gbase) + (voff)[_i]), (PG8_LAS unsigned*)(lds + (bufoff) + ldsw + _i * 8192), 16, 0, 0); } while (0)
; #define PG8_LDA(dst, b, h) do { _Pragma("unroll") for (int m = 0; m < 4; ++m) _Pragma("unroll") for (int k = 0; k < 2; ++k) dst[m][k] = *(const PG8_LAS bf16x8*)(lds + PG8_SA(b, h) + aoff + m * 2048 + k * 1024); } while (0)
; #define PG8_LDB(dst, b, h) do { _Pragma("unroll") for (int n = 0; n < 2; ++n) _Pragma("unroll") for (int k = 0; k < 2; ++k) dst[n][k] = *(const PG8_LAS bf16x8*)(lds + PG8_SB(b, h) + boff + n * 2048 + k * 1024); } while (0)
; #define PG8_MMA(ai, bj, At, Bt) do { __builtin_amdgcn_s_setprio(1); _Pragma("unroll") for (int m = 0; m < 4; ++m) _Pragma("unroll") for (int n = 0; n < 2; ++n) _Pragma("unroll") for (int k = 0; k < 2; ++k) \
;         acc[ai][bj][m][n] = __builtin_amdgcn_mfma_f32_16x16x32_bf16(Bt[n][k], At[m][k], acc[ai][bj][m][n], 0, 0, 0); __builtin_amdgcn_s_setprio(0); } while (0)
; #define PG8_WAIT_V(n) asm volatile("s_waitcnt vmcnt(" #n ")" ::: "memory")
; #define PG8_WAIT_L(n) asm volatile("s_waitcnt lgkmcnt(" #n ")" ::: "memory")
; #define PG8_BAR __builtin_amdgcn_s_barrier()
; #define PG8_SCHED __builtin_amdgcn_sched_barrier(0)
; template <class Epi, class Sched, bool ALIGN_EPI = false, bool SP2 = false>
; __device__ __forceinline__ void gemm_phase(PG8_LAS unsigned char* lds, const Gemm g, const Sched& S, const Epi& E, const int tid_in) {
;     ...
;             PG8_LDA(At, 0, 1); PG8_STAGE(PG8_SB(0, 0), b2, voffB); PG8_STAGE(PG8_SB(0, 1), b2 + hstep, voffB); PG8_STAGE(PG8_SA(0, 0), a2, voffA);
;             PG8_WAIT_V(8); PG8_WAIT_L(0); PG8_BAR; PG8_MMA(1, 0, At, B0); PG8_MMA(1, 1, At, B1); PG8_BAR; PG8_SCHED;
;             PG8_LDB(B0, 1, 0); PG8_LDB(B1, 1, 1); PG8_SCHED; PG8_LDA(At, 1, 0); PG8_STAGE(PG8_SA(0, 1), a2 + hstep, voffA);
;             PG8_WAIT_V(8); PG8_WAIT_L(0); PG8_BAR; PG8_MMA(0, 0, At, B0); PG8_MMA(0, 1, At, B1); PG8_BAR; PG8_SCHED;
.Ltsgu_join_1:
	s_waitcnt lgkmcnt(0)
	s_barrier
	v_mfma_f32_16x16x32_bf16 v[66:69], v[150:153], v[182:185], v[66:69]
	v_mfma_f32_16x16x32_bf16 v[66:69], v[154:157], v[186:189], v[66:69]
	v_mfma_f32_16x16x32_bf16 v[50:53], v[150:153], v[190:193], v[50:53]
	v_mfma_f32_16x16x32_bf16 v[50:53], v[154:157], v[198:201], v[50:53]
	v_mfma_f32_16x16x32_bf16 v[34:37], v[150:153], v[202:205], v[34:37]
	v_mfma_f32_16x16x32_bf16 v[34:37], v[154:157], v[206:209], v[34:37]
	v_mfma_f32_16x16x32_bf16 v[18:21], v[150:153], v[210:213], v[18:21]
	v_mfma_f32_16x16x32_bf16 v[18:21], v[154:157], v[214:217], v[18:21]
	v_mfma_f32_16x16x32_bf16 v[62:65], v[158:161], v[182:185], v[62:65]
	v_mfma_f32_16x16x32_bf16 v[62:65], v[162:165], v[186:189], v[62:65]
	v_mfma_f32_16x16x32_bf16 v[46:49], v[158:161], v[190:193], v[46:49]
	v_mfma_f32_16x16x32_bf16 v[46:49], v[162:165], v[198:201], v[46:49]
	v_mfma_f32_16x16x32_bf16 v[30:33], v[158:161], v[202:205], v[30:33]
	v_mfma_f32_16x16x32_bf16 v[30:33], v[162:165], v[206:209], v[30:33]
	v_mfma_f32_16x16x32_bf16 v[14:17], v[158:161], v[210:213], v[14:17]
	v_mfma_f32_16x16x32_bf16 v[14:17], v[162:165], v[214:217], v[14:17]
	v_mfma_f32_16x16x32_bf16 v[58:61], v[166:169], v[182:185], v[58:61]
	v_mfma_f32_16x16x32_bf16 v[58:61], v[170:173], v[186:189], v[58:61]
	v_mfma_f32_16x16x32_bf16 v[42:45], v[166:169], v[190:193], v[42:45]
	v_mfma_f32_16x16x32_bf16 v[42:45], v[170:173], v[198:201], v[42:45]
	v_mfma_f32_16x16x32_bf16 v[26:29], v[166:169], v[202:205], v[26:29]
	v_mfma_f32_16x16x32_bf16 v[26:29], v[170:173], v[206:209], v[26:29]
	v_mfma_f32_16x16x32_bf16 v[10:13], v[166:169], v[210:213], v[10:13]
	v_mfma_f32_16x16x32_bf16 v[10:13], v[170:173], v[214:217], v[10:13]
	v_mfma_f32_16x16x32_bf16 v[54:57], v[174:177], v[182:185], v[54:57]
	v_mfma_f32_16x16x32_bf16 v[54:57], v[178:181], v[186:189], v[54:57]
	v_mfma_f32_16x16x32_bf16 v[38:41], v[174:177], v[190:193], v[38:41]
	v_mfma_f32_16x16x32_bf16 v[38:41], v[178:181], v[198:201], v[38:41]
	v_mfma_f32_16x16x32_bf16 v[22:25], v[174:177], v[202:205], v[22:25]
	v_mfma_f32_16x16x32_bf16 v[22:25], v[178:181], v[206:209], v[22:25]
	v_mfma_f32_16x16x32_bf16 v[6:9], v[174:177], v[210:213], v[6:9]
	v_mfma_f32_16x16x32_bf16 v[6:9], v[178:181], v[214:217], v[6:9]
	s_barrier
	s_add_i32 s46, 0, 0x18000
	v_add_u32_e32 v149, s46, v146
	s_add_i32 s47, 0, 0x1c000
	ds_read_b128 v[150:153], v149
	ds_read_b128 v[154:157], v149 offset:1024
	ds_read_b128 v[158:161], v149 offset:2048
	ds_read_b128 v[162:165], v149 offset:3072
	v_add_u32_e32 v149, s47, v146
	ds_read_b128 v[166:169], v149
	ds_read_b128 v[170:173], v149 offset:1024
	ds_read_b128 v[174:177], v149 offset:2048
	ds_read_b128 v[178:181], v149 offset:3072
	s_add_u32 s14, s14, 0x40000
	s_addc_u32 s15, s15, 0
	s_mov_b32 m0, s22
	v_lshl_add_u64 v[224:225], s[14:15], 0, v[138:139]
	ds_read_b128 v[182:185], v148 offset:32768
	ds_read_b128 v[186:189], v148 offset:33792
	ds_read_b128 v[190:193], v148 offset:34816
	ds_read_b128 v[198:201], v148 offset:35840
	ds_read_b128 v[202:205], v148 offset:36864
	ds_read_b128 v[206:209], v148 offset:37888
	ds_read_b128 v[210:213], v148 offset:38912
	ds_read_b128 v[214:217], v148 offset:39936
	s_cbranch_vccnz .Ltsgu_skip_2
	global_load_lds_dwordx4 v[224:225], off
	v_lshl_add_u64 v[224:225], s[14:15], 0, v[134:135]
	s_mov_b32 m0, s23
	s_nop 0
	global_load_lds_dwordx4 v[224:225], off
	s_nop 0
	s_waitcnt vmcnt(8)
	s_branch .Ltsgu_join_2

; #define PG8_STAGE(bufoff, gbase, voff) do { _Pragma("unroll") for (int _i = 0; _i < 2; ++_i) \
;         __builtin_amdgcn_global_load_lds((const unsigned*)((const char*)(gbase) + (voff)[_i]), (PG8_LAS unsigned*)(lds + (bufoff) + ldsw + _i * 8192), 16, 0, 0); } while (0)
; #define PG8_LDA(dst, b, h) do { _Pragma("unroll") for (int m = 0; m < 4; ++m) _Pragma("unroll") for (int k = 0; k < 2; ++k) dst[m][k] = *(const PG8_LAS bf16x8*)(lds + PG8_SA(b, h) + aoff + m * 2048 + k * 1024); } while (0)
; #define PG8_MMA(ai, bj, At, Bt) do { __builtin_amdgcn_s_setprio(1); _Pragma("unroll") for (int m = 0; m < 4; ++m) _Pragma("unroll") for (int n = 0; n < 2; ++n) _Pragma("unroll") for (int k = 0; k < 2; ++k) \
;         acc[ai][bj][m][n] = __builtin_amdgcn_mfma_f32_16x16x32_bf16(Bt[n][k], At[m][k], acc[ai][bj][m][n], 0, 0, 0); __builtin_amdgcn_s_setprio(0); } while (0)
; #define PG8_WAIT_V(n) asm volatile("s_waitcnt vmcnt(" #n ")" ::: "memory")
; #define PG8_WAIT_L(n) asm volatile("s_waitcnt lgkmcnt(" #n ")" ::: "memory")
; #define PG8_BAR __builtin_amdgcn_s_barrier()
; #define PG8_SCHED __builtin_amdgcn_sched_barrier(0)
; template <class Epi, class Sched, bool ALIGN_EPI = false, bool SP2 = false>
; __device__ __forceinline__ void gemm_phase(PG8_LAS unsigned char* lds, const Gemm g, const Sched& S, const Epi& E, const int tid_in) {
;     ...
;             PG8_WAIT_V(8); PG8_WAIT_L(0); PG8_BAR; PG8_MMA(0, 0, At, B0); PG8_MMA(0, 1, At, B1); PG8_BAR; PG8_SCHED;
;             PG8_LDA(At, 1, 1); PG8_STAGE(PG8_SB(1, 0), b3, voffB); PG8_STAGE(PG8_SB(1, 1), b3 + hstep, voffB); PG8_STAGE(PG8_SA(1, 0), a3, voffA);
;             PG8_WAIT_V(8); PG8_WAIT_L(0); PG8_BAR; PG8_MMA(1, 0, At, B0); PG8_MMA(1, 1, At, B1); PG8_BAR; PG8_SCHED;
.Ltsgu_join_2:
	s_waitcnt lgkmcnt(0)
	s_barrier
	v_mfma_f32_16x16x32_bf16 v[130:133], v[150:153], v[182:185], v[130:133]
	v_mfma_f32_16x16x32_bf16 v[130:133], v[154:157], v[186:189], v[130:133]
	v_mfma_f32_16x16x32_bf16 v[114:117], v[150:153], v[190:193], v[114:117]
	v_mfma_f32_16x16x32_bf16 v[114:117], v[154:157], v[198:201], v[114:117]
	v_mfma_f32_16x16x32_bf16 v[98:101], v[150:153], v[202:205], v[98:101]
	v_mfma_f32_16x16x32_bf16 v[98:101], v[154:157], v[206:209], v[98:101]
	v_mfma_f32_16x16x32_bf16 v[82:85], v[150:153], v[210:213], v[82:85]
	v_mfma_f32_16x16x32_bf16 v[82:85], v[154:157], v[214:217], v[82:85]
	v_mfma_f32_16x16x32_bf16 v[126:129], v[158:161], v[182:185], v[126:129]
	v_mfma_f32_16x16x32_bf16 v[126:129], v[162:165], v[186:189], v[126:129]
	v_mfma_f32_16x16x32_bf16 v[106:109], v[158:161], v[190:193], v[106:109]
	v_mfma_f32_16x16x32_bf16 v[106:109], v[162:165], v[198:201], v[106:109]
	v_mfma_f32_16x16x32_bf16 v[94:97], v[158:161], v[202:205], v[94:97]
	v_mfma_f32_16x16x32_bf16 v[94:97], v[162:165], v[206:209], v[94:97]
	v_mfma_f32_16x16x32_bf16 v[78:81], v[158:161], v[210:213], v[78:81]
	v_mfma_f32_16x16x32_bf16 v[78:81], v[162:165], v[214:217], v[78:81]
	v_mfma_f32_16x16x32_bf16 v[122:125], v[166:169], v[182:185], v[122:125]
	v_mfma_f32_16x16x32_bf16 v[122:125], v[170:173], v[186:189], v[122:125]
	v_mfma_f32_16x16x32_bf16 v[110:113], v[166:169], v[190:193], v[110:113]
	v_mfma_f32_16x16x32_bf16 v[110:113], v[170:173], v[198:201], v[110:113]
	v_mfma_f32_16x16x32_bf16 v[90:93], v[166:169], v[202:205], v[90:93]
	v_mfma_f32_16x16x32_bf16 v[90:93], v[170:173], v[206:209], v[90:93]
	v_mfma_f32_16x16x32_bf16 v[74:77], v[166:169], v[210:213], v[74:77]
	v_mfma_f32_16x16x32_bf16 v[74:77], v[170:173], v[214:217], v[74:77]
	v_mfma_f32_16x16x32_bf16 v[118:121], v[174:177], v[182:185], v[118:121]
	v_mfma_f32_16x16x32_bf16 v[118:121], v[178:181], v[186:189], v[118:121]
	v_mfma_f32_16x16x32_bf16 v[102:105], v[174:177], v[190:193], v[102:105]
	v_mfma_f32_16x16x32_bf16 v[102:105], v[178:181], v[198:201], v[102:105]
	v_mfma_f32_16x16x32_bf16 v[86:89], v[174:177], v[202:205], v[86:89]
	v_mfma_f32_16x16x32_bf16 v[86:89], v[178:181], v[206:209], v[86:89]
	v_mfma_f32_16x16x32_bf16 v[70:73], v[174:177], v[210:213], v[70:73]
	v_mfma_f32_16x16x32_bf16 v[70:73], v[178:181], v[214:217], v[70:73]
	s_barrier
	s_add_i32 s14, s46, s17
	v_lshl_add_u64 v[144:145], v[144:145], 0, s[28:29]
	s_mov_b32 m0, s14
	ds_read_b128 v[182:185], v148 offset:49152
	ds_read_b128 v[186:189], v148 offset:50176
	ds_read_b128 v[190:193], v148 offset:51200
	ds_read_b128 v[198:201], v148 offset:52224
	ds_read_b128 v[202:205], v148 offset:53248
	ds_read_b128 v[206:209], v148 offset:54272
	ds_read_b128 v[210:213], v148 offset:55296
	ds_read_b128 v[214:217], v148 offset:56320
	s_cbranch_vccnz .Ltsgu_skip_3
	global_load_lds_dwordx4 v[144:145], off
	s_add_i32 m0, s14, 0x2000
	s_add_u32 s12, s12, 0x40080
	v_lshl_add_u64 v[144:145], v[218:219], 0, s[28:29]
	s_addc_u32 s13, s13, 0
	s_add_i32 s14, s47, s17
	global_load_lds_dwordx4 v[144:145], off
	v_lshl_add_u64 v[144:145], s[12:13], 0, v[136:137]
	s_mov_b32 m0, s14
	s_nop 0
	global_load_lds_dwordx4 v[144:145], off
	v_lshl_add_u64 v[144:145], s[12:13], 0, v[2:3]
	s_add_i32 m0, s14, 0x2000
	s_nop 0
	global_load_lds_dwordx4 v[144:145], off
	v_lshl_add_u64 v[144:145], v[220:221], 0, s[28:29]
	s_mov_b32 m0, s26
	s_nop 0
	global_load_lds_dwordx4 v[144:145], off
	v_lshl_add_u64 v[144:145], v[222:223], 0, s[28:29]
	s_mov_b32 m0, s27
	s_nop 0
	global_load_lds_dwordx4 v[144:145], off
	s_nop 0
	s_waitcnt vmcnt(8)
	s_branch .Ltsgu_join_3

; #define PG8_STAGE(bufoff, gbase, voff) do { _Pragma("unroll") for (int _i = 0; _i < 2; ++_i) \
;         __builtin_amdgcn_global_load_lds((const unsigned*)((const char*)(gbase) + (voff)[_i]), (PG8_LAS unsigned*)(lds + (bufoff) + ldsw + _i * 8192), 16, 0, 0); } while (0)
; #define PG8_LDA(dst, b, h) do { _Pragma("unroll") for (int m = 0; m < 4; ++m) _Pragma("unroll") for (int k = 0; k < 2; ++k) dst[m][k] = *(const PG8_LAS bf16x8*)(lds + PG8_SA(b, h) + aoff + m * 2048 + k * 1024); } while (0)
; #define PG8_MMA(ai, bj, At, Bt) do { __builtin_amdgcn_s_setprio(1); _Pragma("unroll") for (int m = 0; m < 4; ++m) _Pragma("unroll") for (int n = 0; n < 2; ++n) _Pragma("unroll") for (int k = 0; k < 2; ++k) \
;         acc[ai][bj][m][n] = __builtin_amdgcn_mfma_f32_16x16x32_bf16(Bt[n][k], At[m][k], acc[ai][bj][m][n], 0, 0, 0); __builtin_amdgcn_s_setprio(0); } while (0)
; #define PG8_WAIT_V(n) asm volatile("s_waitcnt vmcnt(" #n ")" ::: "memory")
; #define PG8_WAIT_L(n) asm volatile("s_waitcnt lgkmcnt(" #n ")" ::: "memory")
; #define PG8_BAR __builtin_amdgcn_s_barrier()
; #define PG8_SCHED __builtin_amdgcn_sched_barrier(0)
; template <class Epi, class Sched, bool ALIGN_EPI = false, bool SP2 = false>
; __device__ __forceinline__ void gemm_phase(PG8_LAS unsigned char* lds, const Gemm g, const Sched& S, const Epi& E, const int tid_in) {
;     ...
;             PG8_LDA(At, 1, 1); PG8_STAGE(PG8_SB(1, 0), b3, voffB); PG8_STAGE(PG8_SB(1, 1), b3 + hstep, voffB); PG8_STAGE(PG8_SA(1, 0), a3, voffA);
;             PG8_WAIT_V(8); PG8_WAIT_L(0); PG8_BAR; PG8_MMA(1, 0, At, B0); PG8_MMA(1, 1, At, B1); PG8_BAR; PG8_SCHED;
;     __device__ __forceinline__ void operator()(const f32x4 (&acc)[2][2][4][2], const Unit& u, int wr, int wc, int fr, int fq) const {
;     ...
;         float rs[2][4];
; #pragma unroll
;         for (int ai = 0; ai < 2; ++ai)
; #pragma unroll
;             for (int m = 0; m < 4; ++m) rs[ai][m] = rowss[row0 + ai * HALF + m * 16];
.Ltsgu_join_3:
	s_waitcnt lgkmcnt(0)
	s_cmp_lg_u32 s45, 12
	s_cbranch_scc1 .Lrs_gu_skip
	v_lshl_add_u32 v144, s40, 8, v5
	v_ashrrev_i32_e32 v145, 31, v144
	v_lshl_add_u64 v[144:145], v[144:145], 2, s[6:7]
	global_load_dword v226, v[144:145], off
	global_load_dword v227, v[144:145], off offset:64
	global_load_dword v228, v[144:145], off offset:128
	global_load_dword v229, v[144:145], off offset:192
	global_load_dword v238, v[144:145], off offset:512
	global_load_dword v239, v[144:145], off offset:576
	global_load_dword v240, v[144:145], off offset:640
	global_load_dword v241, v[144:145], off offset:704
